# v112 + one s_nop before the scan job loop so the chunk-loop head lands on a 64-byte boundary
# baseline (speedup 1.0000x reference)
.LBB0_602:
	s_or_b64 exec, exec, s[0:1]
	s_add_i32 s33, s33, s30
	s_cmpk_gt_i32 s33, 0xff
	s_barrier
	s_cbranch_scc1 .LBB0_732
	s_nop 0
